# grid barrier: flat top level - every XCD leader bumps every XCD's generation word after its write-back, workgroups leave at word >= nx*generation+1; no returning top-level atomic, no last-XCD hop
# speedup vs baseline: 1.0178x; 1.0074x over previous
.LBB0_142:
	s_cmp_lt_i32 s89, 3
	s_cbranch_scc1 .LBB0_188
	s_waitcnt vmcnt(0) lgkmcnt(0)
	s_barrier
	v_readlane_b32 s0, v254, 0
	v_readlane_b32 s4, v254, 6
	v_readlane_b32 s5, v254, 5
	s_andn2_b32 s0, s0, 63
	s_cmp_lg_u32 s0, 0
	s_cbranch_scc1 .Lnb_end_1
	s_mov_b64 s[2:3], exec
	s_mov_b64 exec, 1
	v_mov_b32_e32 v0, s4
	v_mov_b32_e32 v4, 1
	v_mov_b32_e32 v5, 0
	ds_read_b64 v[2:3], v0
	s_lshl_b32 s6, s5, 8
	s_add_u32 s8, s84, s6
	s_addc_u32 s9, s85, 0
	s_add_u32 s16, s8, 0x2400
	s_addc_u32 s17, s9, 0
	s_add_u32 s8, s8, 0x1400
	s_addc_u32 s9, s9, 0
	s_add_u32 s20, s84, 0x3400
	s_addc_u32 s21, s85, 0
	s_add_u32 s26, s84, 0x2400
	s_addc_u32 s27, s85, 0
	s_mov_b32 s24, 0
	global_atomic_add v6, v5, v4, s[8:9] sc0
	buffer_inv sc1
	s_add_u32 s13, s98, 1
	s_waitcnt vmcnt(1) lgkmcnt(0)
	v_readfirstlane_b32 s10, v6
	v_readfirstlane_b32 s11, v2
	v_readfirstlane_b32 s12, v3
	s_add_u32 s10, s10, 1
	s_mul_i32 s14, s13, s11
	s_mul_i32 s23, s12, s98
	s_add_u32 s23, s23, 1
	s_cmp_eq_u32 s10, s14
	s_cbranch_scc1 .Lnb_leader_1
.Lnb_spin_1:
	s_sleep 1
	global_load_dword v7, v5, s[16:17] sc1
	s_waitcnt vmcnt(0)
	v_readfirstlane_b32 s18, v7
	s_cmp_ge_u32 s18, s23
	s_cbranch_scc1 .Lnb_acq_1
	s_add_u32 s24, s24, 1
	s_and_b32 s25, s24, 0xff
	s_cmp_lg_u32 s25, 0
	s_cbranch_scc1 .Lnb_spin_1
	global_load_dword v9, v5, s[84:85] offset:512 sc1
	s_waitcnt vmcnt(0)
	v_readfirstlane_b32 s25, v9
	s_cmp_lg_u32 s25, 0
	s_cbranch_scc1 .Lnb_acq_1
	s_cmp_lt_u32 s24, 0x40001
	s_cbranch_scc1 .Lnb_spin_1
	global_atomic_add v5, v4, s[84:85] offset:512
	s_branch .Lnb_acq_1
.Lnb_leader_1:
	buffer_wbl2 sc1
	s_waitcnt vmcnt(0)
	global_atomic_add v5, v4, s[26:27] offset:0
	global_atomic_add v5, v4, s[26:27] offset:256
	global_atomic_add v5, v4, s[26:27] offset:512
	global_atomic_add v5, v4, s[26:27] offset:768
	global_atomic_add v5, v4, s[26:27] offset:1024
	global_atomic_add v5, v4, s[26:27] offset:1280
	global_atomic_add v5, v4, s[26:27] offset:1536
	global_atomic_add v5, v4, s[26:27] offset:1792
	global_atomic_add v5, v4, s[26:27] offset:2048
	global_atomic_add v5, v4, s[26:27] offset:2304
	global_atomic_add v5, v4, s[26:27] offset:2560
	global_atomic_add v5, v4, s[26:27] offset:2816
	global_atomic_add v5, v4, s[26:27] offset:3072
	global_atomic_add v5, v4, s[26:27] offset:3328
	global_atomic_add v5, v4, s[26:27] offset:3584
	global_atomic_add v5, v4, s[26:27] offset:3840
	s_nop 0
	s_nop 0
	s_nop 0
	s_nop 0
	s_nop 0
	s_branch .Lnb_spin_1

.LBB0_512:
	s_cmp_lt_i32 s89, 4
	s_cbranch_scc1 .LBB0_558
	s_waitcnt vmcnt(0) lgkmcnt(0)
	s_barrier
	v_readlane_b32 s0, v254, 0
	v_readlane_b32 s4, v254, 6
	v_readlane_b32 s5, v254, 5
	s_andn2_b32 s0, s0, 63
	s_cmp_lg_u32 s0, 0
	s_cbranch_scc1 .Lnb_end_2
	s_mov_b64 s[2:3], exec
	s_mov_b64 exec, 1
	v_mov_b32_e32 v0, s4
	v_mov_b32_e32 v4, 1
	v_mov_b32_e32 v5, 0
	ds_read_b64 v[2:3], v0
	s_lshl_b32 s6, s5, 8
	s_add_u32 s8, s84, s6
	s_addc_u32 s9, s85, 0
	s_add_u32 s16, s8, 0x2400
	s_addc_u32 s17, s9, 0
	s_add_u32 s8, s8, 0x1400
	s_addc_u32 s9, s9, 0
	s_add_u32 s20, s84, 0x3400
	s_addc_u32 s21, s85, 0
	s_add_u32 s26, s84, 0x2400
	s_addc_u32 s27, s85, 0
	s_mov_b32 s24, 0
	global_atomic_add v6, v5, v4, s[8:9] sc0
	buffer_inv sc1
	s_add_u32 s13, s98, 1
	s_waitcnt vmcnt(1) lgkmcnt(0)
	v_readfirstlane_b32 s10, v6
	v_readfirstlane_b32 s11, v2
	v_readfirstlane_b32 s12, v3
	s_add_u32 s10, s10, 1
	s_mul_i32 s14, s13, s11
	s_mul_i32 s23, s12, s98
	s_add_u32 s23, s23, 1
	s_cmp_eq_u32 s10, s14
	s_cbranch_scc1 .Lnb_leader_2

.LBB0_857:
	s_cmp_lt_i32 s89, 5
	s_barrier
	s_cbranch_scc1 .LBB0_906
	s_waitcnt vmcnt(0) lgkmcnt(0)
	s_barrier
	v_readlane_b32 s0, v254, 0
	v_readlane_b32 s4, v254, 6
	v_readlane_b32 s5, v254, 5
	s_andn2_b32 s0, s0, 63
	s_cmp_lg_u32 s0, 0
	s_cbranch_scc1 .Lnb_end_3
	s_mov_b64 s[2:3], exec
	s_mov_b64 exec, 1
	v_mov_b32_e32 v0, s4
	v_mov_b32_e32 v4, 1
	v_mov_b32_e32 v5, 0
	ds_read_b64 v[2:3], v0
	s_lshl_b32 s6, s5, 8
	s_add_u32 s8, s84, s6
	s_addc_u32 s9, s85, 0
	s_add_u32 s16, s8, 0x2400
	s_addc_u32 s17, s9, 0
	s_add_u32 s8, s8, 0x1400
	s_addc_u32 s9, s9, 0
	s_add_u32 s20, s84, 0x3400
	s_addc_u32 s21, s85, 0
	s_add_u32 s26, s84, 0x2400
	s_addc_u32 s27, s85, 0
	s_mov_b32 s24, 0
	global_atomic_add v6, v5, v4, s[8:9] sc0
	buffer_inv sc1
	s_add_u32 s13, s98, 1
	s_waitcnt vmcnt(1) lgkmcnt(0)
	v_readfirstlane_b32 s10, v6
	v_readfirstlane_b32 s11, v2
	v_readfirstlane_b32 s12, v3
	s_add_u32 s10, s10, 1
	s_mul_i32 s14, s13, s11
	s_mul_i32 s23, s12, s98
	s_add_u32 s23, s23, 1
	s_cmp_eq_u32 s10, s14
	s_cbranch_scc1 .Lnb_leader_3

.LBB0_933:
	s_cmp_lt_i32 s89, 6
	s_cbranch_scc1 .LBB0_979
	s_waitcnt vmcnt(0) lgkmcnt(0)
	s_barrier
	v_readlane_b32 s0, v254, 0
	v_readlane_b32 s4, v254, 6
	v_readlane_b32 s5, v254, 5
	s_andn2_b32 s0, s0, 63
	s_cmp_lg_u32 s0, 0
	s_cbranch_scc1 .Lnb_end_4
	s_mov_b64 s[2:3], exec
	s_mov_b64 exec, 1
	v_mov_b32_e32 v0, s4
	v_mov_b32_e32 v4, 1
	v_mov_b32_e32 v5, 0
	ds_read_b64 v[2:3], v0
	s_lshl_b32 s6, s5, 8
	s_add_u32 s8, s84, s6
	s_addc_u32 s9, s85, 0
	s_add_u32 s16, s8, 0x2400
	s_addc_u32 s17, s9, 0
	s_add_u32 s8, s8, 0x1400
	s_addc_u32 s9, s9, 0
	s_add_u32 s20, s84, 0x3400
	s_addc_u32 s21, s85, 0
	s_add_u32 s26, s84, 0x2400
	s_addc_u32 s27, s85, 0
	s_mov_b32 s24, 0
	global_atomic_add v6, v5, v4, s[8:9] sc0
	buffer_inv sc1
	s_add_u32 s13, s98, 1
	s_waitcnt vmcnt(1) lgkmcnt(0)
	v_readfirstlane_b32 s10, v6
	v_readfirstlane_b32 s11, v2
	v_readfirstlane_b32 s12, v3
	s_add_u32 s10, s10, 1
	s_mul_i32 s14, s13, s11
	s_mul_i32 s23, s12, s98
	s_add_u32 s23, s23, 1
	s_cmp_eq_u32 s10, s14
	s_cbranch_scc1 .Lnb_leader_4

.LBB0_1175:
	s_cmp_lt_i32 s89, 7
	s_cbranch_scc1 .LBB0_1221
	s_waitcnt vmcnt(0) lgkmcnt(0)
	s_barrier
	v_readlane_b32 s0, v254, 0
	v_readlane_b32 s4, v254, 6
	v_readlane_b32 s5, v254, 5
	s_andn2_b32 s0, s0, 63
	s_cmp_lg_u32 s0, 0
	s_cbranch_scc1 .Lnb_end_5
	s_mov_b64 s[2:3], exec
	s_mov_b64 exec, 1
	v_mov_b32_e32 v0, s4
	v_mov_b32_e32 v4, 1
	v_mov_b32_e32 v5, 0
	ds_read_b64 v[2:3], v0
	s_lshl_b32 s6, s5, 8
	s_add_u32 s8, s84, s6
	s_addc_u32 s9, s85, 0
	s_add_u32 s16, s8, 0x2400
	s_addc_u32 s17, s9, 0
	s_add_u32 s8, s8, 0x1400
	s_addc_u32 s9, s9, 0
	s_add_u32 s20, s84, 0x3400
	s_addc_u32 s21, s85, 0
	s_add_u32 s26, s84, 0x2400
	s_addc_u32 s27, s85, 0
	s_mov_b32 s24, 0
	global_atomic_add v6, v5, v4, s[8:9] sc0
	buffer_inv sc1
	s_add_u32 s13, s98, 1
	s_waitcnt vmcnt(1) lgkmcnt(0)
	v_readfirstlane_b32 s10, v6
	v_readfirstlane_b32 s11, v2
	v_readfirstlane_b32 s12, v3
	s_add_u32 s10, s10, 1
	s_mul_i32 s14, s13, s11
	s_mul_i32 s23, s12, s98
	s_add_u32 s23, s23, 1
	s_cmp_eq_u32 s10, s14
	s_cbranch_scc1 .Lnb_leader_5

.LBB0_1237:
	s_cmp_lt_i32 s89, 8
	s_barrier
	s_cbranch_scc1 .LBB0_1283
	s_waitcnt vmcnt(0) lgkmcnt(0)
	s_barrier
	v_readlane_b32 s0, v254, 0
	v_readlane_b32 s4, v254, 6
	v_readlane_b32 s5, v254, 5
	s_andn2_b32 s0, s0, 63
	s_cmp_lg_u32 s0, 0
	s_cbranch_scc1 .Lnb_end_6
	s_mov_b64 s[2:3], exec
	s_mov_b64 exec, 1
	v_mov_b32_e32 v0, s4
	v_mov_b32_e32 v4, 1
	v_mov_b32_e32 v5, 0
	ds_read_b64 v[2:3], v0
	s_lshl_b32 s6, s5, 8
	s_add_u32 s8, s84, s6
	s_addc_u32 s9, s85, 0
	s_add_u32 s16, s8, 0x2400
	s_addc_u32 s17, s9, 0
	s_add_u32 s8, s8, 0x1400
	s_addc_u32 s9, s9, 0
	s_add_u32 s20, s84, 0x3400
	s_addc_u32 s21, s85, 0
	s_add_u32 s26, s84, 0x2400
	s_addc_u32 s27, s85, 0
	s_mov_b32 s24, 0
	global_atomic_add v6, v5, v4, s[8:9] sc0
	buffer_inv sc1
	s_add_u32 s13, s98, 1
	s_waitcnt vmcnt(1) lgkmcnt(0)
	v_readfirstlane_b32 s10, v6
	v_readfirstlane_b32 s11, v2
	v_readfirstlane_b32 s12, v3
	s_add_u32 s10, s10, 1
	s_mul_i32 s14, s13, s11
	s_mul_i32 s23, s12, s98
	s_add_u32 s23, s23, 1
	s_cmp_eq_u32 s10, s14
	s_cbranch_scc1 .Lnb_leader_6

.LBB0_1308:
	s_cmp_lt_i32 s89, 9
	s_cbranch_scc1 .LBB0_1354
	s_waitcnt vmcnt(0) lgkmcnt(0)
	s_barrier
	v_readlane_b32 s0, v254, 0
	v_readlane_b32 s4, v254, 6
	v_readlane_b32 s5, v254, 5
	s_andn2_b32 s0, s0, 63
	s_cmp_lg_u32 s0, 0
	s_cbranch_scc1 .Lnb_end_7
	s_mov_b64 s[2:3], exec
	s_mov_b64 exec, 1
	v_mov_b32_e32 v0, s4
	v_mov_b32_e32 v4, 1
	v_mov_b32_e32 v5, 0
	ds_read_b64 v[2:3], v0
	s_lshl_b32 s6, s5, 8
	s_add_u32 s8, s84, s6
	s_addc_u32 s9, s85, 0
	s_add_u32 s16, s8, 0x2400
	s_addc_u32 s17, s9, 0
	s_add_u32 s8, s8, 0x1400
	s_addc_u32 s9, s9, 0
	s_add_u32 s20, s84, 0x3400
	s_addc_u32 s21, s85, 0
	s_add_u32 s26, s84, 0x2400
	s_addc_u32 s27, s85, 0
	s_mov_b32 s24, 0
	global_atomic_add v6, v5, v4, s[8:9] sc0
	buffer_inv sc1
	s_add_u32 s13, s98, 1
	s_waitcnt vmcnt(1) lgkmcnt(0)
	v_readfirstlane_b32 s10, v6
	v_readfirstlane_b32 s11, v2
	v_readfirstlane_b32 s12, v3
	s_add_u32 s10, s10, 1
	s_mul_i32 s14, s13, s11
	s_mul_i32 s23, s12, s98
	s_add_u32 s23, s23, 1
	s_cmp_eq_u32 s10, s14
	s_cbranch_scc1 .Lnb_leader_7

.LBB0_1481:
	s_cmp_lt_i32 s89, 10
	s_cbranch_scc1 .LBB0_1527
	s_waitcnt vmcnt(0) lgkmcnt(0)
	s_barrier
	v_readlane_b32 s0, v254, 0
	v_readlane_b32 s4, v254, 6
	v_readlane_b32 s5, v254, 5
	s_andn2_b32 s0, s0, 63
	s_cmp_lg_u32 s0, 0
	s_cbranch_scc1 .Lnb_end_8
	s_mov_b64 s[2:3], exec
	s_mov_b64 exec, 1
	v_mov_b32_e32 v0, s4
	v_mov_b32_e32 v4, 1
	v_mov_b32_e32 v5, 0
	ds_read_b64 v[2:3], v0
	s_lshl_b32 s6, s5, 8
	s_add_u32 s8, s84, s6
	s_addc_u32 s9, s85, 0
	s_add_u32 s16, s8, 0x2400
	s_addc_u32 s17, s9, 0
	s_add_u32 s8, s8, 0x1400
	s_addc_u32 s9, s9, 0
	s_add_u32 s20, s84, 0x3400
	s_addc_u32 s21, s85, 0
	s_add_u32 s26, s84, 0x2400
	s_addc_u32 s27, s85, 0
	s_mov_b32 s24, 0
	global_atomic_add v6, v5, v4, s[8:9] sc0
	buffer_inv sc1
	s_add_u32 s13, s98, 1
	s_waitcnt vmcnt(1) lgkmcnt(0)
	v_readfirstlane_b32 s10, v6
	v_readfirstlane_b32 s11, v2
	v_readfirstlane_b32 s12, v3
	s_add_u32 s10, s10, 1
	s_mul_i32 s14, s13, s11
	s_mul_i32 s23, s12, s98
	s_add_u32 s23, s23, 1
	s_cmp_eq_u32 s10, s14
	s_cbranch_scc1 .Lnb_leader_8

.LBB0_1563:
	s_cmp_lt_i32 s89, 11
	s_barrier
	s_cbranch_scc1 .LBB0_1609
	s_waitcnt vmcnt(0) lgkmcnt(0)
	s_barrier
	v_readlane_b32 s0, v254, 0
	v_readlane_b32 s4, v254, 6
	v_readlane_b32 s5, v254, 5
	s_andn2_b32 s0, s0, 63
	s_cmp_lg_u32 s0, 0
	s_cbranch_scc1 .Lnb_end_9
	s_mov_b64 s[2:3], exec
	s_mov_b64 exec, 1
	v_mov_b32_e32 v0, s4
	v_mov_b32_e32 v4, 1
	v_mov_b32_e32 v5, 0
	ds_read_b64 v[2:3], v0
	s_lshl_b32 s6, s5, 8
	s_add_u32 s8, s84, s6
	s_addc_u32 s9, s85, 0
	s_add_u32 s16, s8, 0x2400
	s_addc_u32 s17, s9, 0
	s_add_u32 s8, s8, 0x1400
	s_addc_u32 s9, s9, 0
	s_add_u32 s20, s84, 0x3400
	s_addc_u32 s21, s85, 0
	s_add_u32 s26, s84, 0x2400
	s_addc_u32 s27, s85, 0
	s_mov_b32 s24, 0
	global_atomic_add v6, v5, v4, s[8:9] sc0
	buffer_inv sc1
	s_add_u32 s13, s98, 1
	s_waitcnt vmcnt(1) lgkmcnt(0)
	v_readfirstlane_b32 s10, v6
	v_readfirstlane_b32 s11, v2
	v_readfirstlane_b32 s12, v3
	s_add_u32 s10, s10, 1
	s_mul_i32 s14, s13, s11
	s_mul_i32 s23, s12, s98
	s_add_u32 s23, s23, 1
	s_cmp_eq_u32 s10, s14
	s_cbranch_scc1 .Lnb_leader_9

.LBB0_1651:
	s_cmp_lt_i32 s89, 12
	s_cbranch_scc1 .LBB0_1697
	s_waitcnt vmcnt(0) lgkmcnt(0)
	s_barrier
	v_readlane_b32 s0, v254, 0
	v_readlane_b32 s4, v254, 6
	v_readlane_b32 s5, v254, 5
	s_andn2_b32 s0, s0, 63
	s_cmp_lg_u32 s0, 0
	s_cbranch_scc1 .Lnb_end_10
	s_mov_b64 s[2:3], exec
	s_mov_b64 exec, 1
	v_mov_b32_e32 v0, s4
	v_mov_b32_e32 v4, 1
	v_mov_b32_e32 v5, 0
	ds_read_b64 v[2:3], v0
	s_lshl_b32 s6, s5, 8
	s_add_u32 s8, s84, s6
	s_addc_u32 s9, s85, 0
	s_add_u32 s16, s8, 0x2400
	s_addc_u32 s17, s9, 0
	s_add_u32 s8, s8, 0x1400
	s_addc_u32 s9, s9, 0
	s_add_u32 s20, s84, 0x3400
	s_addc_u32 s21, s85, 0
	s_add_u32 s26, s84, 0x2400
	s_addc_u32 s27, s85, 0
	s_mov_b32 s24, 0
	global_atomic_add v6, v5, v4, s[8:9] sc0
	buffer_inv sc1
	s_add_u32 s13, s98, 1
	s_waitcnt vmcnt(1) lgkmcnt(0)
	v_readfirstlane_b32 s10, v6
	v_readfirstlane_b32 s11, v2
	v_readfirstlane_b32 s12, v3
	s_add_u32 s10, s10, 1
	s_mul_i32 s14, s13, s11
	s_mul_i32 s23, s12, s98
	s_add_u32 s23, s23, 1
	s_cmp_eq_u32 s10, s14
	s_cbranch_scc1 .Lnb_leader_10

.LBB0_2021:
	s_cmp_lt_i32 s89, 13
	s_cbranch_scc1 .LBB0_2067
	s_waitcnt vmcnt(0) lgkmcnt(0)
	s_barrier
	v_readlane_b32 s0, v254, 0
	v_readlane_b32 s4, v254, 6
	v_readlane_b32 s5, v254, 5
	s_andn2_b32 s0, s0, 63
	s_cmp_lg_u32 s0, 0
	s_cbranch_scc1 .Lnb_end_11
	s_mov_b64 s[2:3], exec
	s_mov_b64 exec, 1
	v_mov_b32_e32 v0, s4
	v_mov_b32_e32 v4, 1
	v_mov_b32_e32 v5, 0
	ds_read_b64 v[2:3], v0
	s_lshl_b32 s6, s5, 8
	s_add_u32 s8, s84, s6
	s_addc_u32 s9, s85, 0
	s_add_u32 s16, s8, 0x2400
	s_addc_u32 s17, s9, 0
	s_add_u32 s8, s8, 0x1400
	s_addc_u32 s9, s9, 0
	s_add_u32 s20, s84, 0x3400
	s_addc_u32 s21, s85, 0
	s_add_u32 s26, s84, 0x2400
	s_addc_u32 s27, s85, 0
	s_mov_b32 s24, 0
	global_atomic_add v6, v5, v4, s[8:9] sc0
	buffer_inv sc1
	s_add_u32 s13, s98, 1
	s_waitcnt vmcnt(1) lgkmcnt(0)
	v_readfirstlane_b32 s10, v6
	v_readfirstlane_b32 s11, v2
	v_readfirstlane_b32 s12, v3
	s_add_u32 s10, s10, 1
	s_mul_i32 s14, s13, s11
	s_mul_i32 s23, s12, s98
	s_add_u32 s23, s23, 1
	s_cmp_eq_u32 s10, s14
	s_cbranch_scc1 .Lnb_leader_11

.LBB0_2366:
	s_cmp_lt_i32 s89, 14
	s_barrier
	s_cbranch_scc1 .LBB0_2415
	s_waitcnt vmcnt(0) lgkmcnt(0)
	s_barrier
	v_readlane_b32 s0, v254, 0
	v_readlane_b32 s4, v254, 6
	v_readlane_b32 s5, v254, 5
	s_andn2_b32 s0, s0, 63
	s_cmp_lg_u32 s0, 0
	s_cbranch_scc1 .Lnb_end_12
	s_mov_b64 s[2:3], exec
	s_mov_b64 exec, 1
	v_mov_b32_e32 v0, s4
	v_mov_b32_e32 v4, 1
	v_mov_b32_e32 v5, 0
	ds_read_b64 v[2:3], v0
	s_lshl_b32 s6, s5, 8
	s_add_u32 s8, s84, s6
	s_addc_u32 s9, s85, 0
	s_add_u32 s16, s8, 0x2400
	s_addc_u32 s17, s9, 0
	s_add_u32 s8, s8, 0x1400
	s_addc_u32 s9, s9, 0
	s_add_u32 s20, s84, 0x3400
	s_addc_u32 s21, s85, 0
	s_add_u32 s26, s84, 0x2400
	s_addc_u32 s27, s85, 0
	s_mov_b32 s24, 0
	global_atomic_add v6, v5, v4, s[8:9] sc0
	buffer_inv sc1
	s_add_u32 s13, s98, 1
	s_waitcnt vmcnt(1) lgkmcnt(0)
	v_readfirstlane_b32 s10, v6
	v_readfirstlane_b32 s11, v2
	v_readfirstlane_b32 s12, v3
	s_add_u32 s10, s10, 1
	s_mul_i32 s14, s13, s11
	s_mul_i32 s23, s12, s98
	s_add_u32 s23, s23, 1
	s_cmp_eq_u32 s10, s14
	s_cbranch_scc1 .Lnb_leader_12

.LBB0_2442:
	s_cmp_lt_i32 s89, 15
	s_cbranch_scc1 .LBB0_2488
	s_waitcnt vmcnt(0) lgkmcnt(0)
	s_barrier
	v_readlane_b32 s0, v254, 0
	v_readlane_b32 s4, v254, 6
	v_readlane_b32 s5, v254, 5
	s_andn2_b32 s0, s0, 63
	s_cmp_lg_u32 s0, 0
	s_cbranch_scc1 .Lnb_end_13
	s_mov_b64 s[2:3], exec
	s_mov_b64 exec, 1
	v_mov_b32_e32 v0, s4
	v_mov_b32_e32 v4, 1
	v_mov_b32_e32 v5, 0
	ds_read_b64 v[2:3], v0
	s_lshl_b32 s6, s5, 8
	s_add_u32 s8, s84, s6
	s_addc_u32 s9, s85, 0
	s_add_u32 s16, s8, 0x2400
	s_addc_u32 s17, s9, 0
	s_add_u32 s8, s8, 0x1400
	s_addc_u32 s9, s9, 0
	s_add_u32 s20, s84, 0x3400
	s_addc_u32 s21, s85, 0
	s_add_u32 s26, s84, 0x2400
	s_addc_u32 s27, s85, 0
	s_mov_b32 s24, 0
	global_atomic_add v6, v5, v4, s[8:9] sc0
	buffer_inv sc1
	s_add_u32 s13, s98, 1
	s_waitcnt vmcnt(1) lgkmcnt(0)
	v_readfirstlane_b32 s10, v6
	v_readfirstlane_b32 s11, v2
	v_readfirstlane_b32 s12, v3
	s_add_u32 s10, s10, 1
	s_mul_i32 s14, s13, s11
	s_mul_i32 s23, s12, s98
	s_add_u32 s23, s23, 1
	s_cmp_eq_u32 s10, s14
	s_cbranch_scc1 .Lnb_leader_13

.LBB0_2611:
	s_cmp_lt_i32 s89, 16
	s_cbranch_scc1 .LBB0_2657
	s_waitcnt vmcnt(0) lgkmcnt(0)
	s_barrier
	v_readlane_b32 s0, v254, 0
	v_readlane_b32 s4, v254, 6
	v_readlane_b32 s5, v254, 5
	s_andn2_b32 s0, s0, 63
	s_cmp_lg_u32 s0, 0
	s_cbranch_scc1 .Lnb_end_14
	s_mov_b64 s[2:3], exec
	s_mov_b64 exec, 1
	v_mov_b32_e32 v0, s4
	v_mov_b32_e32 v4, 1
	v_mov_b32_e32 v5, 0
	ds_read_b64 v[2:3], v0
	s_lshl_b32 s6, s5, 8
	s_add_u32 s8, s84, s6
	s_addc_u32 s9, s85, 0
	s_add_u32 s16, s8, 0x2400
	s_addc_u32 s17, s9, 0
	s_add_u32 s8, s8, 0x1400
	s_addc_u32 s9, s9, 0
	s_add_u32 s20, s84, 0x3400
	s_addc_u32 s21, s85, 0
	s_add_u32 s26, s84, 0x2400
	s_addc_u32 s27, s85, 0
	s_mov_b32 s24, 0
	global_atomic_add v6, v5, v4, s[8:9] sc0
	buffer_inv sc1
	s_add_u32 s13, s98, 1
	s_waitcnt vmcnt(1) lgkmcnt(0)
	v_readfirstlane_b32 s10, v6
	v_readfirstlane_b32 s11, v2
	v_readfirstlane_b32 s12, v3
	s_add_u32 s10, s10, 1
	s_mul_i32 s14, s13, s11
	s_mul_i32 s23, s12, s98
	s_add_u32 s23, s23, 1
	s_cmp_eq_u32 s10, s14
	s_cbranch_scc1 .Lnb_leader_14

.LBB0_2665:
	s_cmp_lt_i32 s89, 17
	s_barrier
	s_cbranch_scc1 .LBB0_2711
	s_waitcnt vmcnt(0) lgkmcnt(0)
	s_barrier
	v_readlane_b32 s0, v254, 0
	v_readlane_b32 s4, v254, 6
	v_readlane_b32 s5, v254, 5
	s_andn2_b32 s0, s0, 63
	s_cmp_lg_u32 s0, 0
	s_cbranch_scc1 .Lnb_end_15
	s_mov_b64 s[2:3], exec
	s_mov_b64 exec, 1
	v_mov_b32_e32 v0, s4
	v_mov_b32_e32 v4, 1
	v_mov_b32_e32 v5, 0
	ds_read_b64 v[2:3], v0
	s_lshl_b32 s6, s5, 8
	s_add_u32 s8, s84, s6
	s_addc_u32 s9, s85, 0
	s_add_u32 s16, s8, 0x2400
	s_addc_u32 s17, s9, 0
	s_add_u32 s8, s8, 0x1400
	s_addc_u32 s9, s9, 0
	s_add_u32 s20, s84, 0x3400
	s_addc_u32 s21, s85, 0
	s_add_u32 s26, s84, 0x2400
	s_addc_u32 s27, s85, 0
	s_mov_b32 s24, 0
	global_atomic_add v6, v5, v4, s[8:9] sc0
	buffer_inv sc1
	s_add_u32 s13, s98, 1
	s_waitcnt vmcnt(1) lgkmcnt(0)
	v_readfirstlane_b32 s10, v6
	v_readfirstlane_b32 s11, v2
	v_readfirstlane_b32 s12, v3
	s_add_u32 s10, s10, 1
	s_mul_i32 s14, s13, s11
	s_mul_i32 s23, s12, s98
	s_add_u32 s23, s23, 1
	s_cmp_eq_u32 s10, s14
	s_cbranch_scc1 .Lnb_leader_15

.LBB0_2736:
	s_cmp_lt_i32 s89, 18
	s_cbranch_scc1 .LBB0_2782
	s_waitcnt vmcnt(0) lgkmcnt(0)
	s_barrier
	v_readlane_b32 s0, v254, 0
	v_readlane_b32 s4, v254, 6
	v_readlane_b32 s5, v254, 5
	s_andn2_b32 s0, s0, 63
	s_cmp_lg_u32 s0, 0
	s_cbranch_scc1 .Lnb_end_16
	s_mov_b64 s[2:3], exec
	s_mov_b64 exec, 1
	v_mov_b32_e32 v0, s4
	v_mov_b32_e32 v4, 1
	v_mov_b32_e32 v5, 0
	ds_read_b64 v[2:3], v0
	s_lshl_b32 s6, s5, 8
	s_add_u32 s8, s84, s6
	s_addc_u32 s9, s85, 0
	s_add_u32 s16, s8, 0x2400
	s_addc_u32 s17, s9, 0
	s_add_u32 s8, s8, 0x1400
	s_addc_u32 s9, s9, 0
	s_add_u32 s20, s84, 0x3400
	s_addc_u32 s21, s85, 0
	s_add_u32 s26, s84, 0x2400
	s_addc_u32 s27, s85, 0
	s_mov_b32 s24, 0
	global_atomic_add v6, v5, v4, s[8:9] sc0
	buffer_inv sc1
	s_add_u32 s13, s98, 1
	s_waitcnt vmcnt(1) lgkmcnt(0)
	v_readfirstlane_b32 s10, v6
	v_readfirstlane_b32 s11, v2
	v_readfirstlane_b32 s12, v3
	s_add_u32 s10, s10, 1
	s_mul_i32 s14, s13, s11
	s_mul_i32 s23, s12, s98
	s_add_u32 s23, s23, 1
	s_cmp_eq_u32 s10, s14
	s_cbranch_scc1 .Lnb_leader_16

.LBB0_2918:
	s_cmp_lt_i32 s89, 19
	s_cbranch_scc1 .LBB0_2980
	s_waitcnt vmcnt(0) lgkmcnt(0)
	s_barrier
	v_readlane_b32 s0, v254, 0
	v_readlane_b32 s4, v254, 6
	v_readlane_b32 s5, v254, 5
	s_andn2_b32 s0, s0, 63
	s_cmp_lg_u32 s0, 0
	s_cbranch_scc1 .Lnb_end_17
	s_mov_b64 s[2:3], exec
	s_mov_b64 exec, 1
	v_mov_b32_e32 v0, s4
	v_mov_b32_e32 v4, 1
	v_mov_b32_e32 v5, 0
	ds_read_b64 v[2:3], v0
	s_lshl_b32 s6, s5, 8
	s_add_u32 s8, s84, s6
	s_addc_u32 s9, s85, 0
	s_add_u32 s16, s8, 0x2400
	s_addc_u32 s17, s9, 0
	s_add_u32 s8, s8, 0x1400
	s_addc_u32 s9, s9, 0
	s_add_u32 s20, s84, 0x3400
	s_addc_u32 s21, s85, 0
	s_add_u32 s26, s84, 0x2400
	s_addc_u32 s27, s85, 0
	s_mov_b32 s24, 0
	global_atomic_add v6, v5, v4, s[8:9] sc0
	buffer_inv sc1
	s_add_u32 s13, s98, 1
	s_waitcnt vmcnt(1) lgkmcnt(0)
	v_readfirstlane_b32 s10, v6
	v_readfirstlane_b32 s11, v2
	v_readfirstlane_b32 s12, v3
	s_add_u32 s10, s10, 1
	s_mul_i32 s14, s13, s11
	s_mul_i32 s23, s12, s98
	s_add_u32 s23, s23, 1
	s_cmp_eq_u32 s10, s14
	s_cbranch_scc1 .Lnb_leader_17
